# P0: adaLN strip loop issues all 13 w_ada row loads up front (was load+vmcnt(0) per iteration)
# baseline (speedup 1.0000x reference)
; __global__ void __launch_bounds__(NWAVES * 64, 2) fwd_megakernel(Params P) {
;     ...
;         for (int strip = bx; strip < 256; strip += G) {
;             const int cgi = tid % 6, kk = tid / 6;
;             if (kk < 85) {
;                 f32x4 a[6];
; #pragma unroll
;                 for (int s = 0; s < 6; ++s) a[s] = (f32x4){0.f, 0.f, 0.f, 0.f};
;                 for (int k = kk; k < 1024; k += 85) { const f32x4 w = *(const f32x4*)(P.in[5] + (size_t)k * 6144 + strip * 24 + cgi * 4);
; #pragma unroll
;                     for (int s = 0; s < 6; ++s) a[s] += w * sc[s * 1024 + k]; }
.LBB0_47:
	v_mov_b32_e32 v208, 0xffffffaf
	s_mov_b64 s[16:17], 0x17e8000
	v_cmp_gt_i32_e64 s[4:5], v208, v35
	v_lshl_add_u64 v[206:207], v[32:33], 0, s[16:17]
	s_and_saveexec_b64 s[16:17], s[4:5]
	global_load_dwordx4 v[202:205], v[206:207], off
	s_or_b64 exec, exec, s[16:17]
	global_load_dwordx4 v[154:157], v[32:33], off
	v_lshl_add_u64 v[32:33], v[32:33], 0, s[12:13]
	global_load_dwordx4 v[158:161], v[32:33], off
	v_lshl_add_u64 v[32:33], v[32:33], 0, s[12:13]
	global_load_dwordx4 v[162:165], v[32:33], off
	v_lshl_add_u64 v[32:33], v[32:33], 0, s[12:13]
	global_load_dwordx4 v[166:169], v[32:33], off
	v_lshl_add_u64 v[32:33], v[32:33], 0, s[12:13]
	global_load_dwordx4 v[170:173], v[32:33], off
	v_lshl_add_u64 v[32:33], v[32:33], 0, s[12:13]
	global_load_dwordx4 v[174:177], v[32:33], off
	v_lshl_add_u64 v[32:33], v[32:33], 0, s[12:13]
	global_load_dwordx4 v[178:181], v[32:33], off
	v_lshl_add_u64 v[32:33], v[32:33], 0, s[12:13]
	global_load_dwordx4 v[182:185], v[32:33], off
	v_lshl_add_u64 v[32:33], v[32:33], 0, s[12:13]
	global_load_dwordx4 v[186:189], v[32:33], off
	v_lshl_add_u64 v[32:33], v[32:33], 0, s[12:13]
	global_load_dwordx4 v[190:193], v[32:33], off
	v_lshl_add_u64 v[32:33], v[32:33], 0, s[12:13]
	global_load_dwordx4 v[194:197], v[32:33], off
	v_lshl_add_u64 v[32:33], v[32:33], 0, s[12:13]
	global_load_dwordx4 v[198:201], v[32:33], off
	ds_read2st64_b32 v[128:129], v122 offset1:16
	ds_read2st64_b32 v[130:131], v122 offset0:32 offset1:48
	ds_read2st64_b32 v[132:133], v122 offset0:64 offset1:80
	s_waitcnt lgkmcnt(2)
	v_mov_b32_e32 v134, v129
	s_waitcnt lgkmcnt(1)
	v_mov_b32_e32 v136, v131
	s_waitcnt lgkmcnt(0)
	v_mov_b32_e32 v138, v133
	v_add_u32_e32 v122, 0x154, v122
	s_waitcnt vmcnt(11)
	v_pk_fma_f32 v[4:5], v[156:157], v[128:129], v[4:5] op_sel_hi:[1,0,1]
	v_pk_fma_f32 v[2:3], v[154:155], v[128:129], v[2:3] op_sel_hi:[1,0,1]
	v_pk_fma_f32 v[8:9], v[156:157], v[134:135], v[8:9] op_sel_hi:[1,0,1]
	v_pk_fma_f32 v[6:7], v[154:155], v[134:135], v[6:7] op_sel_hi:[1,0,1]
	v_pk_fma_f32 v[12:13], v[156:157], v[130:131], v[12:13] op_sel_hi:[1,0,1]
	v_pk_fma_f32 v[10:11], v[154:155], v[130:131], v[10:11] op_sel_hi:[1,0,1]
	v_pk_fma_f32 v[16:17], v[156:157], v[136:137], v[16:17] op_sel_hi:[1,0,1]
	v_pk_fma_f32 v[14:15], v[154:155], v[136:137], v[14:15] op_sel_hi:[1,0,1]
	v_pk_fma_f32 v[20:21], v[156:157], v[132:133], v[20:21] op_sel_hi:[1,0,1]
	v_pk_fma_f32 v[18:19], v[154:155], v[132:133], v[18:19] op_sel_hi:[1,0,1]
	v_pk_fma_f32 v[24:25], v[156:157], v[138:139], v[24:25] op_sel_hi:[1,0,1]
	v_pk_fma_f32 v[22:23], v[154:155], v[138:139], v[22:23] op_sel_hi:[1,0,1]
	ds_read2st64_b32 v[128:129], v122 offset1:16
	ds_read2st64_b32 v[130:131], v122 offset0:32 offset1:48
	ds_read2st64_b32 v[132:133], v122 offset0:64 offset1:80
	s_waitcnt lgkmcnt(2)
	v_mov_b32_e32 v134, v129
	s_waitcnt lgkmcnt(1)
	v_mov_b32_e32 v136, v131
	s_waitcnt lgkmcnt(0)
	v_mov_b32_e32 v138, v133
	v_add_u32_e32 v122, 0x154, v122
	s_waitcnt vmcnt(10)
	v_pk_fma_f32 v[4:5], v[160:161], v[128:129], v[4:5] op_sel_hi:[1,0,1]
	v_pk_fma_f32 v[2:3], v[158:159], v[128:129], v[2:3] op_sel_hi:[1,0,1]
	v_pk_fma_f32 v[8:9], v[160:161], v[134:135], v[8:9] op_sel_hi:[1,0,1]
	v_pk_fma_f32 v[6:7], v[158:159], v[134:135], v[6:7] op_sel_hi:[1,0,1]
	v_pk_fma_f32 v[12:13], v[160:161], v[130:131], v[12:13] op_sel_hi:[1,0,1]
	v_pk_fma_f32 v[10:11], v[158:159], v[130:131], v[10:11] op_sel_hi:[1,0,1]
	v_pk_fma_f32 v[16:17], v[160:161], v[136:137], v[16:17] op_sel_hi:[1,0,1]
	v_pk_fma_f32 v[14:15], v[158:159], v[136:137], v[14:15] op_sel_hi:[1,0,1]
	v_pk_fma_f32 v[20:21], v[160:161], v[132:133], v[20:21] op_sel_hi:[1,0,1]
	v_pk_fma_f32 v[18:19], v[158:159], v[132:133], v[18:19] op_sel_hi:[1,0,1]
	v_pk_fma_f32 v[24:25], v[160:161], v[138:139], v[24:25] op_sel_hi:[1,0,1]
	v_pk_fma_f32 v[22:23], v[158:159], v[138:139], v[22:23] op_sel_hi:[1,0,1]
	ds_read2st64_b32 v[128:129], v122 offset1:16
	ds_read2st64_b32 v[130:131], v122 offset0:32 offset1:48
	ds_read2st64_b32 v[132:133], v122 offset0:64 offset1:80
	s_waitcnt lgkmcnt(2)
	v_mov_b32_e32 v134, v129
	s_waitcnt lgkmcnt(1)
	v_mov_b32_e32 v136, v131
	s_waitcnt lgkmcnt(0)
	v_mov_b32_e32 v138, v133
	v_add_u32_e32 v122, 0x154, v122
	s_waitcnt vmcnt(9)
	v_pk_fma_f32 v[4:5], v[164:165], v[128:129], v[4:5] op_sel_hi:[1,0,1]
	v_pk_fma_f32 v[2:3], v[162:163], v[128:129], v[2:3] op_sel_hi:[1,0,1]
	v_pk_fma_f32 v[8:9], v[164:165], v[134:135], v[8:9] op_sel_hi:[1,0,1]
	v_pk_fma_f32 v[6:7], v[162:163], v[134:135], v[6:7] op_sel_hi:[1,0,1]
	v_pk_fma_f32 v[12:13], v[164:165], v[130:131], v[12:13] op_sel_hi:[1,0,1]
	v_pk_fma_f32 v[10:11], v[162:163], v[130:131], v[10:11] op_sel_hi:[1,0,1]
	v_pk_fma_f32 v[16:17], v[164:165], v[136:137], v[16:17] op_sel_hi:[1,0,1]
	v_pk_fma_f32 v[14:15], v[162:163], v[136:137], v[14:15] op_sel_hi:[1,0,1]
	v_pk_fma_f32 v[20:21], v[164:165], v[132:133], v[20:21] op_sel_hi:[1,0,1]
	v_pk_fma_f32 v[18:19], v[162:163], v[132:133], v[18:19] op_sel_hi:[1,0,1]
	v_pk_fma_f32 v[24:25], v[164:165], v[138:139], v[24:25] op_sel_hi:[1,0,1]
	v_pk_fma_f32 v[22:23], v[162:163], v[138:139], v[22:23] op_sel_hi:[1,0,1]
	ds_read2st64_b32 v[128:129], v122 offset1:16
	ds_read2st64_b32 v[130:131], v122 offset0:32 offset1:48
	ds_read2st64_b32 v[132:133], v122 offset0:64 offset1:80
	s_waitcnt lgkmcnt(2)
	v_mov_b32_e32 v134, v129
	s_waitcnt lgkmcnt(1)
	v_mov_b32_e32 v136, v131
	s_waitcnt lgkmcnt(0)
	v_mov_b32_e32 v138, v133
	v_add_u32_e32 v122, 0x154, v122
	s_waitcnt vmcnt(8)
; __global__ void __launch_bounds__(NWAVES * 64, 2) fwd_megakernel(Params P) {
;     ...
;                 for (int k = kk; k < 1024; k += 85) { const f32x4 w = *(const f32x4*)(P.in[5] + (size_t)k * 6144 + strip * 24 + cgi * 4);
; #pragma unroll
;                     for (int s = 0; s < 6; ++s) a[s] += w * sc[s * 1024 + k]; }
	v_pk_fma_f32 v[4:5], v[168:169], v[128:129], v[4:5] op_sel_hi:[1,0,1]
	v_pk_fma_f32 v[2:3], v[166:167], v[128:129], v[2:3] op_sel_hi:[1,0,1]
	v_pk_fma_f32 v[8:9], v[168:169], v[134:135], v[8:9] op_sel_hi:[1,0,1]
	v_pk_fma_f32 v[6:7], v[166:167], v[134:135], v[6:7] op_sel_hi:[1,0,1]
	v_pk_fma_f32 v[12:13], v[168:169], v[130:131], v[12:13] op_sel_hi:[1,0,1]
	v_pk_fma_f32 v[10:11], v[166:167], v[130:131], v[10:11] op_sel_hi:[1,0,1]
	v_pk_fma_f32 v[16:17], v[168:169], v[136:137], v[16:17] op_sel_hi:[1,0,1]
	v_pk_fma_f32 v[14:15], v[166:167], v[136:137], v[14:15] op_sel_hi:[1,0,1]
	v_pk_fma_f32 v[20:21], v[168:169], v[132:133], v[20:21] op_sel_hi:[1,0,1]
	v_pk_fma_f32 v[18:19], v[166:167], v[132:133], v[18:19] op_sel_hi:[1,0,1]
	v_pk_fma_f32 v[24:25], v[168:169], v[138:139], v[24:25] op_sel_hi:[1,0,1]
	v_pk_fma_f32 v[22:23], v[166:167], v[138:139], v[22:23] op_sel_hi:[1,0,1]
	ds_read2st64_b32 v[128:129], v122 offset1:16
	ds_read2st64_b32 v[130:131], v122 offset0:32 offset1:48
	ds_read2st64_b32 v[132:133], v122 offset0:64 offset1:80
	s_waitcnt lgkmcnt(2)
	v_mov_b32_e32 v134, v129
	s_waitcnt lgkmcnt(1)
	v_mov_b32_e32 v136, v131
	s_waitcnt lgkmcnt(0)
	v_mov_b32_e32 v138, v133
	v_add_u32_e32 v122, 0x154, v122
	s_waitcnt vmcnt(7)
	v_pk_fma_f32 v[4:5], v[172:173], v[128:129], v[4:5] op_sel_hi:[1,0,1]
	v_pk_fma_f32 v[2:3], v[170:171], v[128:129], v[2:3] op_sel_hi:[1,0,1]
	v_pk_fma_f32 v[8:9], v[172:173], v[134:135], v[8:9] op_sel_hi:[1,0,1]
	v_pk_fma_f32 v[6:7], v[170:171], v[134:135], v[6:7] op_sel_hi:[1,0,1]
	v_pk_fma_f32 v[12:13], v[172:173], v[130:131], v[12:13] op_sel_hi:[1,0,1]
	v_pk_fma_f32 v[10:11], v[170:171], v[130:131], v[10:11] op_sel_hi:[1,0,1]
	v_pk_fma_f32 v[16:17], v[172:173], v[136:137], v[16:17] op_sel_hi:[1,0,1]
	v_pk_fma_f32 v[14:15], v[170:171], v[136:137], v[14:15] op_sel_hi:[1,0,1]
	v_pk_fma_f32 v[20:21], v[172:173], v[132:133], v[20:21] op_sel_hi:[1,0,1]
	v_pk_fma_f32 v[18:19], v[170:171], v[132:133], v[18:19] op_sel_hi:[1,0,1]
	v_pk_fma_f32 v[24:25], v[172:173], v[138:139], v[24:25] op_sel_hi:[1,0,1]
	v_pk_fma_f32 v[22:23], v[170:171], v[138:139], v[22:23] op_sel_hi:[1,0,1]
	ds_read2st64_b32 v[128:129], v122 offset1:16
	ds_read2st64_b32 v[130:131], v122 offset0:32 offset1:48
	ds_read2st64_b32 v[132:133], v122 offset0:64 offset1:80
	s_waitcnt lgkmcnt(2)
	v_mov_b32_e32 v134, v129
	s_waitcnt lgkmcnt(1)
	v_mov_b32_e32 v136, v131
	s_waitcnt lgkmcnt(0)
	v_mov_b32_e32 v138, v133
	v_add_u32_e32 v122, 0x154, v122
	s_waitcnt vmcnt(6)
	v_pk_fma_f32 v[4:5], v[176:177], v[128:129], v[4:5] op_sel_hi:[1,0,1]
	v_pk_fma_f32 v[2:3], v[174:175], v[128:129], v[2:3] op_sel_hi:[1,0,1]
	v_pk_fma_f32 v[8:9], v[176:177], v[134:135], v[8:9] op_sel_hi:[1,0,1]
	v_pk_fma_f32 v[6:7], v[174:175], v[134:135], v[6:7] op_sel_hi:[1,0,1]
	v_pk_fma_f32 v[12:13], v[176:177], v[130:131], v[12:13] op_sel_hi:[1,0,1]
	v_pk_fma_f32 v[10:11], v[174:175], v[130:131], v[10:11] op_sel_hi:[1,0,1]
	v_pk_fma_f32 v[16:17], v[176:177], v[136:137], v[16:17] op_sel_hi:[1,0,1]
	v_pk_fma_f32 v[14:15], v[174:175], v[136:137], v[14:15] op_sel_hi:[1,0,1]
	v_pk_fma_f32 v[20:21], v[176:177], v[132:133], v[20:21] op_sel_hi:[1,0,1]
	v_pk_fma_f32 v[18:19], v[174:175], v[132:133], v[18:19] op_sel_hi:[1,0,1]
	v_pk_fma_f32 v[24:25], v[176:177], v[138:139], v[24:25] op_sel_hi:[1,0,1]
	v_pk_fma_f32 v[22:23], v[174:175], v[138:139], v[22:23] op_sel_hi:[1,0,1]
	ds_read2st64_b32 v[128:129], v122 offset1:16
	ds_read2st64_b32 v[130:131], v122 offset0:32 offset1:48
	ds_read2st64_b32 v[132:133], v122 offset0:64 offset1:80
	s_waitcnt lgkmcnt(2)
	v_mov_b32_e32 v134, v129
	s_waitcnt lgkmcnt(1)
	v_mov_b32_e32 v136, v131
	s_waitcnt lgkmcnt(0)
	v_mov_b32_e32 v138, v133
	v_add_u32_e32 v122, 0x154, v122
	s_waitcnt vmcnt(5)
	v_pk_fma_f32 v[4:5], v[180:181], v[128:129], v[4:5] op_sel_hi:[1,0,1]
	v_pk_fma_f32 v[2:3], v[178:179], v[128:129], v[2:3] op_sel_hi:[1,0,1]
	v_pk_fma_f32 v[8:9], v[180:181], v[134:135], v[8:9] op_sel_hi:[1,0,1]
	v_pk_fma_f32 v[6:7], v[178:179], v[134:135], v[6:7] op_sel_hi:[1,0,1]
	v_pk_fma_f32 v[12:13], v[180:181], v[130:131], v[12:13] op_sel_hi:[1,0,1]
	v_pk_fma_f32 v[10:11], v[178:179], v[130:131], v[10:11] op_sel_hi:[1,0,1]
	v_pk_fma_f32 v[16:17], v[180:181], v[136:137], v[16:17] op_sel_hi:[1,0,1]
	v_pk_fma_f32 v[14:15], v[178:179], v[136:137], v[14:15] op_sel_hi:[1,0,1]
	v_pk_fma_f32 v[20:21], v[180:181], v[132:133], v[20:21] op_sel_hi:[1,0,1]
	v_pk_fma_f32 v[18:19], v[178:179], v[132:133], v[18:19] op_sel_hi:[1,0,1]
	v_pk_fma_f32 v[24:25], v[180:181], v[138:139], v[24:25] op_sel_hi:[1,0,1]
	v_pk_fma_f32 v[22:23], v[178:179], v[138:139], v[22:23] op_sel_hi:[1,0,1]
	ds_read2st64_b32 v[128:129], v122 offset1:16
	ds_read2st64_b32 v[130:131], v122 offset0:32 offset1:48
	ds_read2st64_b32 v[132:133], v122 offset0:64 offset1:80
	s_waitcnt lgkmcnt(2)
	v_mov_b32_e32 v134, v129
	s_waitcnt lgkmcnt(1)
	v_mov_b32_e32 v136, v131
	s_waitcnt lgkmcnt(0)
	v_mov_b32_e32 v138, v133
	v_add_u32_e32 v122, 0x154, v122
	s_waitcnt vmcnt(4)
	v_pk_fma_f32 v[4:5], v[184:185], v[128:129], v[4:5] op_sel_hi:[1,0,1]
	v_pk_fma_f32 v[2:3], v[182:183], v[128:129], v[2:3] op_sel_hi:[1,0,1]
	v_pk_fma_f32 v[8:9], v[184:185], v[134:135], v[8:9] op_sel_hi:[1,0,1]
	v_pk_fma_f32 v[6:7], v[182:183], v[134:135], v[6:7] op_sel_hi:[1,0,1]
	v_pk_fma_f32 v[12:13], v[184:185], v[130:131], v[12:13] op_sel_hi:[1,0,1]
	v_pk_fma_f32 v[10:11], v[182:183], v[130:131], v[10:11] op_sel_hi:[1,0,1]
	v_pk_fma_f32 v[16:17], v[184:185], v[136:137], v[16:17] op_sel_hi:[1,0,1]
	v_pk_fma_f32 v[14:15], v[182:183], v[136:137], v[14:15] op_sel_hi:[1,0,1]
	v_pk_fma_f32 v[20:21], v[184:185], v[132:133], v[20:21] op_sel_hi:[1,0,1]
	v_pk_fma_f32 v[18:19], v[182:183], v[132:133], v[18:19] op_sel_hi:[1,0,1]
	v_pk_fma_f32 v[24:25], v[184:185], v[138:139], v[24:25] op_sel_hi:[1,0,1]
	v_pk_fma_f32 v[22:23], v[182:183], v[138:139], v[22:23] op_sel_hi:[1,0,1]
	ds_read2st64_b32 v[128:129], v122 offset1:16
	ds_read2st64_b32 v[130:131], v122 offset0:32 offset1:48
	ds_read2st64_b32 v[132:133], v122 offset0:64 offset1:80
	s_waitcnt lgkmcnt(2)
; #define LAS __attribute__((address_space(3)))
; __global__ void __launch_bounds__(NWAVES * 64, 2) fwd_megakernel(Params P) {
;     ...
;                 for (int k = kk; k < 1024; k += 85) { const f32x4 w = *(const f32x4*)(P.in[5] + (size_t)k * 6144 + strip * 24 + cgi * 4);
; #pragma unroll
;                     for (int s = 0; s < 6; ++s) a[s] += w * sc[s * 1024 + k]; }
; #pragma unroll
;                 for (int s = 0; s < 6; ++s) *(LAS f32x4*)(part + ((kk * 6 + cgi) * 6 + s) * 4) = a[s];
	v_mov_b32_e32 v134, v129
	s_waitcnt lgkmcnt(1)
	v_mov_b32_e32 v136, v131
	s_waitcnt lgkmcnt(0)
	v_mov_b32_e32 v138, v133
	v_add_u32_e32 v122, 0x154, v122
	s_waitcnt vmcnt(3)
	v_pk_fma_f32 v[4:5], v[188:189], v[128:129], v[4:5] op_sel_hi:[1,0,1]
	v_pk_fma_f32 v[2:3], v[186:187], v[128:129], v[2:3] op_sel_hi:[1,0,1]
	v_pk_fma_f32 v[8:9], v[188:189], v[134:135], v[8:9] op_sel_hi:[1,0,1]
	v_pk_fma_f32 v[6:7], v[186:187], v[134:135], v[6:7] op_sel_hi:[1,0,1]
	v_pk_fma_f32 v[12:13], v[188:189], v[130:131], v[12:13] op_sel_hi:[1,0,1]
	v_pk_fma_f32 v[10:11], v[186:187], v[130:131], v[10:11] op_sel_hi:[1,0,1]
	v_pk_fma_f32 v[16:17], v[188:189], v[136:137], v[16:17] op_sel_hi:[1,0,1]
	v_pk_fma_f32 v[14:15], v[186:187], v[136:137], v[14:15] op_sel_hi:[1,0,1]
	v_pk_fma_f32 v[20:21], v[188:189], v[132:133], v[20:21] op_sel_hi:[1,0,1]
	v_pk_fma_f32 v[18:19], v[186:187], v[132:133], v[18:19] op_sel_hi:[1,0,1]
	v_pk_fma_f32 v[24:25], v[188:189], v[138:139], v[24:25] op_sel_hi:[1,0,1]
	v_pk_fma_f32 v[22:23], v[186:187], v[138:139], v[22:23] op_sel_hi:[1,0,1]
	ds_read2st64_b32 v[128:129], v122 offset1:16
	ds_read2st64_b32 v[130:131], v122 offset0:32 offset1:48
	ds_read2st64_b32 v[132:133], v122 offset0:64 offset1:80
	s_waitcnt lgkmcnt(2)
	v_mov_b32_e32 v134, v129
	s_waitcnt lgkmcnt(1)
	v_mov_b32_e32 v136, v131
	s_waitcnt lgkmcnt(0)
	v_mov_b32_e32 v138, v133
	v_add_u32_e32 v122, 0x154, v122
	s_waitcnt vmcnt(2)
	v_pk_fma_f32 v[4:5], v[192:193], v[128:129], v[4:5] op_sel_hi:[1,0,1]
	v_pk_fma_f32 v[2:3], v[190:191], v[128:129], v[2:3] op_sel_hi:[1,0,1]
	v_pk_fma_f32 v[8:9], v[192:193], v[134:135], v[8:9] op_sel_hi:[1,0,1]
	v_pk_fma_f32 v[6:7], v[190:191], v[134:135], v[6:7] op_sel_hi:[1,0,1]
	v_pk_fma_f32 v[12:13], v[192:193], v[130:131], v[12:13] op_sel_hi:[1,0,1]
	v_pk_fma_f32 v[10:11], v[190:191], v[130:131], v[10:11] op_sel_hi:[1,0,1]
	v_pk_fma_f32 v[16:17], v[192:193], v[136:137], v[16:17] op_sel_hi:[1,0,1]
	v_pk_fma_f32 v[14:15], v[190:191], v[136:137], v[14:15] op_sel_hi:[1,0,1]
	v_pk_fma_f32 v[20:21], v[192:193], v[132:133], v[20:21] op_sel_hi:[1,0,1]
	v_pk_fma_f32 v[18:19], v[190:191], v[132:133], v[18:19] op_sel_hi:[1,0,1]
	v_pk_fma_f32 v[24:25], v[192:193], v[138:139], v[24:25] op_sel_hi:[1,0,1]
	v_pk_fma_f32 v[22:23], v[190:191], v[138:139], v[22:23] op_sel_hi:[1,0,1]
	ds_read2st64_b32 v[128:129], v122 offset1:16
	ds_read2st64_b32 v[130:131], v122 offset0:32 offset1:48
	ds_read2st64_b32 v[132:133], v122 offset0:64 offset1:80
	s_waitcnt lgkmcnt(2)
	v_mov_b32_e32 v134, v129
	s_waitcnt lgkmcnt(1)
	v_mov_b32_e32 v136, v131
	s_waitcnt lgkmcnt(0)
	v_mov_b32_e32 v138, v133
	v_add_u32_e32 v122, 0x154, v122
	s_waitcnt vmcnt(1)
	v_pk_fma_f32 v[4:5], v[196:197], v[128:129], v[4:5] op_sel_hi:[1,0,1]
	v_pk_fma_f32 v[2:3], v[194:195], v[128:129], v[2:3] op_sel_hi:[1,0,1]
	v_pk_fma_f32 v[8:9], v[196:197], v[134:135], v[8:9] op_sel_hi:[1,0,1]
	v_pk_fma_f32 v[6:7], v[194:195], v[134:135], v[6:7] op_sel_hi:[1,0,1]
	v_pk_fma_f32 v[12:13], v[196:197], v[130:131], v[12:13] op_sel_hi:[1,0,1]
	v_pk_fma_f32 v[10:11], v[194:195], v[130:131], v[10:11] op_sel_hi:[1,0,1]
	v_pk_fma_f32 v[16:17], v[196:197], v[136:137], v[16:17] op_sel_hi:[1,0,1]
	v_pk_fma_f32 v[14:15], v[194:195], v[136:137], v[14:15] op_sel_hi:[1,0,1]
	v_pk_fma_f32 v[20:21], v[196:197], v[132:133], v[20:21] op_sel_hi:[1,0,1]
	v_pk_fma_f32 v[18:19], v[194:195], v[132:133], v[18:19] op_sel_hi:[1,0,1]
	v_pk_fma_f32 v[24:25], v[196:197], v[138:139], v[24:25] op_sel_hi:[1,0,1]
	v_pk_fma_f32 v[22:23], v[194:195], v[138:139], v[22:23] op_sel_hi:[1,0,1]
	ds_read2st64_b32 v[128:129], v122 offset1:16
	ds_read2st64_b32 v[130:131], v122 offset0:32 offset1:48
	ds_read2st64_b32 v[132:133], v122 offset0:64 offset1:80
	s_waitcnt lgkmcnt(2)
	v_mov_b32_e32 v134, v129
	s_waitcnt lgkmcnt(1)
	v_mov_b32_e32 v136, v131
	s_waitcnt lgkmcnt(0)
	v_mov_b32_e32 v138, v133
	v_add_u32_e32 v122, 0x154, v122
	s_waitcnt vmcnt(0)
	v_pk_fma_f32 v[4:5], v[200:201], v[128:129], v[4:5] op_sel_hi:[1,0,1]
	v_pk_fma_f32 v[2:3], v[198:199], v[128:129], v[2:3] op_sel_hi:[1,0,1]
	v_pk_fma_f32 v[8:9], v[200:201], v[134:135], v[8:9] op_sel_hi:[1,0,1]
	v_pk_fma_f32 v[6:7], v[198:199], v[134:135], v[6:7] op_sel_hi:[1,0,1]
	v_pk_fma_f32 v[12:13], v[200:201], v[130:131], v[12:13] op_sel_hi:[1,0,1]
	v_pk_fma_f32 v[10:11], v[198:199], v[130:131], v[10:11] op_sel_hi:[1,0,1]
	v_pk_fma_f32 v[16:17], v[200:201], v[136:137], v[16:17] op_sel_hi:[1,0,1]
	v_pk_fma_f32 v[14:15], v[198:199], v[136:137], v[14:15] op_sel_hi:[1,0,1]
	v_pk_fma_f32 v[20:21], v[200:201], v[132:133], v[20:21] op_sel_hi:[1,0,1]
	v_pk_fma_f32 v[18:19], v[198:199], v[132:133], v[18:19] op_sel_hi:[1,0,1]
	v_pk_fma_f32 v[24:25], v[200:201], v[138:139], v[24:25] op_sel_hi:[1,0,1]
	v_pk_fma_f32 v[22:23], v[198:199], v[138:139], v[22:23] op_sel_hi:[1,0,1]
	s_and_saveexec_b64 s[16:17], s[4:5]
	ds_read2st64_b32 v[128:129], v122 offset1:16
	ds_read2st64_b32 v[130:131], v122 offset0:32 offset1:48
	ds_read2st64_b32 v[132:133], v122 offset0:64 offset1:80
	s_waitcnt lgkmcnt(2)
	v_mov_b32_e32 v134, v129
	s_waitcnt lgkmcnt(1)
	v_mov_b32_e32 v136, v131
	s_waitcnt lgkmcnt(0)
	v_mov_b32_e32 v138, v133
	v_add_u32_e32 v122, 0x154, v122
	s_waitcnt vmcnt(0)
	v_pk_fma_f32 v[4:5], v[204:205], v[128:129], v[4:5] op_sel_hi:[1,0,1]
	v_pk_fma_f32 v[2:3], v[202:203], v[128:129], v[2:3] op_sel_hi:[1,0,1]
	v_pk_fma_f32 v[8:9], v[204:205], v[134:135], v[8:9] op_sel_hi:[1,0,1]
	v_pk_fma_f32 v[6:7], v[202:203], v[134:135], v[6:7] op_sel_hi:[1,0,1]
	v_pk_fma_f32 v[12:13], v[204:205], v[130:131], v[12:13] op_sel_hi:[1,0,1]
	v_pk_fma_f32 v[10:11], v[202:203], v[130:131], v[10:11] op_sel_hi:[1,0,1]
	v_pk_fma_f32 v[16:17], v[204:205], v[136:137], v[16:17] op_sel_hi:[1,0,1]
	v_pk_fma_f32 v[14:15], v[202:203], v[136:137], v[14:15] op_sel_hi:[1,0,1]
	v_pk_fma_f32 v[20:21], v[204:205], v[132:133], v[20:21] op_sel_hi:[1,0,1]
	v_pk_fma_f32 v[18:19], v[202:203], v[132:133], v[18:19] op_sel_hi:[1,0,1]
	v_pk_fma_f32 v[24:25], v[204:205], v[138:139], v[24:25] op_sel_hi:[1,0,1]
	v_pk_fma_f32 v[22:23], v[202:203], v[138:139], v[22:23] op_sel_hi:[1,0,1]
	s_or_b64 exec, exec, s[16:17]
	s_mov_b64 s[16:17], 0
	s_or_b64 exec, exec, s[16:17]
	ds_write_b128 v37, v[2:5] offset:32768
	ds_write_b128 v37, v[6:9] offset:32784
	ds_write_b128 v37, v[10:13] offset:32800
	ds_write_b128 v37, v[14:17] offset:32816
	ds_write_b128 v37, v[18:21] offset:32832
	ds_write_b128 v37, v[22:25] offset:32848
